# seams PB->PC and PF->PA: conversion-counter poll and group-record poll share one round trip (flag first, both loads, one wait)
# speedup vs baseline: 1.0071x; 1.0071x over previous
; __device__ __forceinline__ unsigned xb_ld(unsigned* p)              { return __hip_atomic_load(p, __ATOMIC_RELAXED, __HIP_MEMORY_SCOPE_AGENT); }
; __device__ __forceinline__ unsigned xb_add(unsigned* p, unsigned v) { return __hip_atomic_fetch_add(p, v, __ATOMIC_RELAXED, __HIP_MEMORY_SCOPE_AGENT); }
; #define XB_SPIN(cond, bar) do { unsigned _sp = 0; while (cond) { __builtin_amdgcn_s_sleep(1); \
;     if ((++_sp & 255u) == 0u) { if (xb_ld(&(bar)[XB_TMO])) break; if (_sp > XB_SPIN_CAP) { atomicAdd(&(bar)[XB_TMO], 1u); break; } } } } while (0)
; #define SEAM_G(k) do { if (IN(k) && IN((k) + 1)) { if (xl_fast) xcc_local_barrier(ctl + CW_BAR2, bar.x, bar.st[0], bar.bar); else xcd_barrier(bar); } } while (0)
; #define SEAM_G(k) SEAM(k)
; __device__ __forceinline__ void xcc_local_barrier(unsigned* bar2, unsigned x, unsigned nloc, unsigned* tmobar) {
;     asm volatile("s_waitcnt vmcnt(0)" ::: "memory");
;     __syncthreads();
;     if (threadIdx.x == 0) {
;         const unsigned old = xb_add(&bar2[XB_XSUB(x)], 1u);
;         const unsigned gen = old / nloc;
;         if (old + 1u == (gen + 1u) * nloc) (void)xb_add(&bar2[XB_XGEN(x)], 1u);
;         else XB_SPIN(xb_ld(&bar2[XB_XGEN(x)]) == gen, tmobar);
;         __builtin_amdgcn_fence(__ATOMIC_ACQUIRE, "agent");
;         asm volatile("s_waitcnt vmcnt(0)" ::: "memory");
;     }
;     __syncthreads();
; }
; __global__ void __launch_bounds__(NWAVES * 64, 2) mk_fwd(Args args) {
;     ...
;         SEAM_G(pb + 1);
.LBB0_478:
	s_and_b64 vcc, exec, s[38:39]
	s_cbranch_vccz .LBB0_498
	v_readlane_b32 s6, v238, 25
	s_nop 1
	v_mov_b32_e32 v2, s6
	ds_read_b32 v2, v2
	s_waitcnt vmcnt(0)
	v_readlane_b32 s6, v242, 38
	v_readlane_b32 s7, v242, 39
	s_waitcnt vmcnt(0) lgkmcnt(0)
	s_barrier
	s_and_saveexec_b64 s[38:39], s[6:7]
	s_cbranch_execz .LBB0_497
	s_cmp_ge_u32 s101, 5
	s_cselect_b32 s88, 2, 1
	s_lshl_b32 s88, s88, 8
	s_add_i32 s101, s101, 1
	v_readlane_b32 s6, v239, 63
	v_readlane_b32 s7, v241, 0
	v_readlane_b32 s98, v242, 4
	v_mov_b32_e32 v3, s101
	s_nop 3
	s_lshr_b32 s98, s98, 6
	s_lshl_b32 s98, s98, 2
	v_mov_b32_e32 v4, s98
	global_store_dword v4, v3, s[6:7] offset:128 sc1
	buffer_inv sc1
	v_readlane_b32 s12, v240, 60
	v_readlane_b32 s13, v240, 61
	s_mov_b32 s100, 0
	s_nop 4
.Lgrp_poll_0:
	global_load_dwordx4 v[4:7], v66, s[6:7] offset:128 sc1
	global_load_dword v3, v66, s[12:13] offset:512 sc1
	s_waitcnt vmcnt(0)
	v_min_u32_e32 v4, v4, v5
	v_min3_u32 v4, v4, v6, v7
	v_cmp_le_u32_e32 vcc, s88, v3
	v_readfirstlane_b32 s98, v4
	s_nop 3
	s_cbranch_vccz .Lgrp_retry_0
	s_cmp_ge_u32 s98, s101
	s_cbranch_scc1 .Lgrp_done_0
.Lgrp_retry_0:
	s_sleep 1
	s_add_i32 s100, s100, 1
	s_cmp_lt_u32 s100, 0x10000
	s_cbranch_scc1 .Lgrp_poll_0

; __device__ __forceinline__ unsigned xb_ld(unsigned* p)              { return __hip_atomic_load(p, __ATOMIC_RELAXED, __HIP_MEMORY_SCOPE_AGENT); }
; __device__ __forceinline__ unsigned xb_add(unsigned* p, unsigned v) { return __hip_atomic_fetch_add(p, v, __ATOMIC_RELAXED, __HIP_MEMORY_SCOPE_AGENT); }
; #define XB_SPIN(cond, bar) do { unsigned _sp = 0; while (cond) { __builtin_amdgcn_s_sleep(1); \
;     if ((++_sp & 255u) == 0u) { if (xb_ld(&(bar)[XB_TMO])) break; if (_sp > XB_SPIN_CAP) { atomicAdd(&(bar)[XB_TMO], 1u); break; } } } } while (0)
; #define SEAM(k) do { if (IN(k) && IN((k) + 1)) { xcd_barrier(bar); xcd_barrier(bar); } } while (0)
; #define SEAM(k) do { if (IN(k) && IN((k) + 1)) xcd_barrier(bar); } while (0)
; #define SEAM_G(k) do { if (IN(k) && IN((k) + 1)) { if (xl_fast) xcc_local_barrier(ctl + CW_BAR2, bar.x, bar.st[0], bar.bar); else xcd_barrier(bar); } } while (0)
; #define SEAM_G(k) SEAM(k)
; __device__ __forceinline__ void xcc_local_barrier(unsigned* bar2, unsigned x, unsigned nloc, unsigned* tmobar) {
;     asm volatile("s_waitcnt vmcnt(0)" ::: "memory");
;     __syncthreads();
;     if (threadIdx.x == 0) {
;         const unsigned old = xb_add(&bar2[XB_XSUB(x)], 1u);
;         const unsigned gen = old / nloc;
;         if (old + 1u == (gen + 1u) * nloc) (void)xb_add(&bar2[XB_XGEN(x)], 1u);
;         else XB_SPIN(xb_ld(&bar2[XB_XGEN(x)]) == gen, tmobar);
;         __builtin_amdgcn_fence(__ATOMIC_ACQUIRE, "agent");
;         asm volatile("s_waitcnt vmcnt(0)" ::: "memory");
;     }
;     __syncthreads();
; }
; __global__ void __launch_bounds__(NWAVES * 64, 2) mk_fwd(Args args) {
;     ...
;         if (l == DEPTH - 1) SEAM_G(pb + 5); else SEAM(pb + 5);
.LBB0_932:
	v_readlane_b32 s6, v238, 44
	s_add_i32 s23, s6, 7
	s_cmp_lt_i32 s23, s5
	v_readlane_b32 s6, v238, 51
	s_cselect_b64 s[24:25], -1, 0
	v_readlane_b32 s7, v238, 52
	s_and_b64 s[36:37], s[42:43], s[24:25]
	s_and_b64 vcc, exec, s[6:7]
	s_cbranch_vccz .LBB0_945
	v_readlane_b32 s28, v240, 2
	s_mov_b64 s[38:39], 0
	s_and_b64 vcc, exec, s[36:37]
	s_mov_b64 s[40:41], 0
	v_readlane_b32 s29, v240, 3
	s_cbranch_vccz .LBB0_946
	s_waitcnt vmcnt(0)
	v_readlane_b32 s6, v242, 38
	v_readlane_b32 s7, v242, 39
	s_waitcnt vmcnt(0) lgkmcnt(0)
	s_barrier
	s_and_saveexec_b64 s[40:41], s[6:7]
	s_cbranch_execz .LBB0_1018
	v_readlane_b32 s6, v242, 52
	v_readlane_b32 s7, v242, 53
	s_nop 3
	s_cmp_eq_u64 s[6:7], 0
	s_cbranch_scc0 .Lpf_seam_grid
	s_add_i32 s101, s101, 1
	v_readlane_b32 s6, v239, 63
	v_readlane_b32 s7, v241, 0
	v_readlane_b32 s98, v242, 4
	v_mov_b32_e32 v3, s101
	s_nop 3
	s_lshr_b32 s98, s98, 6
	s_lshl_b32 s98, s98, 2
	v_mov_b32_e32 v4, s98
	global_store_dword v4, v3, s[6:7] offset:128 sc1
	buffer_inv sc1
	v_readlane_b32 s12, v240, 60
	v_readlane_b32 s13, v240, 61
	s_mov_b32 s100, 0
	s_nop 4
.Lgrp_poll_5:
	global_load_dwordx4 v[4:7], v66, s[6:7] offset:128 sc1
	global_load_dword v3, v66, s[12:13] offset:576 sc1
	s_waitcnt vmcnt(0)
	v_min_u32_e32 v4, v4, v5
	v_min3_u32 v4, v4, v6, v7
	v_cmp_le_u32_e32 vcc, 0x100, v3
	v_readfirstlane_b32 s98, v4
	s_nop 3
	s_cbranch_vccz .Lgrp_retry_5
	s_cmp_ge_u32 s98, s101
	s_cbranch_scc1 .Lgrp_done_5
